# prologue rebalanced to 3 fold/convert waves + 5 stream waves (x stream got faster with nt), otherwise v44
# baseline (speedup 1.0000x reference)
; #define LAS __attribute__((address_space(3)))
; __device__ __forceinline__ u32x4 pack8(const float* f) { u32x4 w; w.x = cvt_pk_bf16(f[0], f[1]); w.y = cvt_pk_bf16(f[2], f[3]); w.z = cvt_pk_bf16(f[4], f[5]); w.w = cvt_pk_bf16(f[6], f[7]); return w; }
; __device__ __forceinline__ void prologue(const Params& p, LAS unsigned char* lds) {
;     const int tid = threadIdx.x, lane = tid & 63, wid = __builtin_amdgcn_readfirstlane(tid >> 6);
;     const int gt = blockIdx.x * 512 + tid, NGT = gridDim.x * 512;
;     float* ssq = (float*)(p.ws + WS_SSQ);
;     for (int i = gt; i < 3 * MPAD; i += NGT) ssq[MPAD + i] = 0.f;
;     {
;         const int gwv = blockIdx.x * 8 + wid, NGWV = gridDim.x * 8;
;         for (int it = gwv; it < 2 * 1024; it += NGWV) {
;             const int l = it >> 10, r = it & 1023, nblk = r & 15, kg = r >> 4, g = kg >> 4, c0 = (kg & 15) * 8, n = nblk * 64 + lane;
;             const float* wp = p.w_pool + ((size_t)l * 4 + g) * 128 * 128 + (size_t)c0 * 128;
;             const float* sc = p.pool_scale + l * 512 + g * 128;
;             const float* wb = p.w_br_pool + (size_t)l * 512 * DM + (size_t)(g * 128) * DM + n;
;             float a[8];
; #pragma unroll
;             for (int i = 0; i < 8; ++i) a[i] = 0.f;
; #pragma unroll 8
;             for (int d = 0; d < 128; ++d) { const float x = wb[(size_t)d * DM] * sc[d];
; #pragma unroll
;                 for (int i = 0; i < 8; ++i) a[i] += wp[i * 128 + d] * x; }
;             bf16_t* dst = (bf16_t*)(p.ws + WS_W + (size_t)l * W_LAYER + WO_MIX) + (size_t)(1024 + n) * 512 + g * 128 + c0;
;             *(u32x4*)dst = pack8(a);
.LBB0_46:
	s_or_b64 exec, exec, s[10:11]
	s_load_dwordx16 s[52:67], s[0:1], 0x0
	s_lshl_b32 s6, s92, 3
	v_and_b32_e32 v39, 63, v222
	v_mov_b32_e32 v1, 0
	s_waitcnt lgkmcnt(0)
	v_writelane_b32 v249, s52, 4
	s_nop 1
	v_writelane_b32 v249, s53, 5
	v_writelane_b32 v249, s54, 6
	v_writelane_b32 v249, s55, 7
	v_writelane_b32 v249, s56, 8
	v_writelane_b32 v249, s57, 9
	v_writelane_b32 v249, s58, 10
	v_writelane_b32 v249, s59, 11
	v_writelane_b32 v249, s60, 12
	v_writelane_b32 v249, s61, 13
	v_writelane_b32 v249, s62, 14
	v_writelane_b32 v249, s63, 15
	v_writelane_b32 v249, s64, 16
	v_writelane_b32 v249, s65, 17
	v_writelane_b32 v249, s66, 18
	v_writelane_b32 v249, s67, 19
	s_load_dwordx16 s[52:67], s[0:1], 0x40
	s_lshl_b32 s0, s81, 3
	s_lshr_b32 s1, s17, 6
	s_add_i32 s0, s1, s0
	s_cmpk_gt_i32 s0, 0x7ff
	s_waitcnt lgkmcnt(0)
	v_writelane_b32 v249, s52, 20
	s_nop 1
	v_writelane_b32 v249, s53, 21
	v_writelane_b32 v249, s54, 22
	v_writelane_b32 v249, s55, 23
	v_writelane_b32 v249, s56, 24
	v_writelane_b32 v249, s57, 25
	v_writelane_b32 v249, s58, 26
	v_writelane_b32 v249, s59, 27
	v_writelane_b32 v249, s60, 28
	v_writelane_b32 v249, s61, 29
	v_writelane_b32 v249, s62, 30
	v_writelane_b32 v249, s63, 31
	v_writelane_b32 v249, s64, 32
	v_writelane_b32 v249, s65, 33
	v_writelane_b32 v249, s66, 34
	v_writelane_b32 v249, s67, 35
	s_cbranch_scc1 .LBB0_51
	s_lshr_b32 s32, s17, 6
	s_cmp_lt_u32 s32, 5
	s_cbranch_scc1 .LBB0_51
	s_lshl_b32 s1, s1, 6
	v_readlane_b32 s52, v249, 20
	s_add_i32 s1, s16, s1
	v_readlane_b32 s58, v249, 26
	v_readlane_b32 s59, v249, 27
	s_add_u32 s9, s58, 28
	s_addc_u32 s18, s59, 0
	s_mov_b32 s5, 0
	s_movk_i32 s19, 0x2000
	s_movk_i32 s20, 0x4000
	s_movk_i32 s21, 0x6000
	s_movk_i32 s23, 0x7000
	s_mov_b32 s24, s0
	s_lshr_b32 s32, s17, 6
	s_add_i32 s32, s32, -5
	s_mul_i32 s24, s81, 3
	s_add_i32 s24, s24, s32
	s_lshl_b32 s1, s24, 6
	s_mul_i32 s32, s92, 3
	s_lshl_b32 s33, s32, 6
	v_readlane_b32 s53, v249, 21
	v_readlane_b32 s54, v249, 22
	v_readlane_b32 s55, v249, 23
	v_readlane_b32 s56, v249, 24
	v_readlane_b32 s57, v249, 25
	v_readlane_b32 s60, v249, 28
	v_readlane_b32 s61, v249, 29
	v_readlane_b32 s62, v249, 30
	v_readlane_b32 s63, v249, 31
	v_readlane_b32 s64, v249, 32
	v_readlane_b32 s65, v249, 33
	v_readlane_b32 s66, v249, 34
	v_readlane_b32 s67, v249, 35

; #define LAS __attribute__((address_space(3)))
; __device__ __forceinline__ void transpose_item(const float* W, int N, const float* ks, bf16_t* WT, int ldo, int orow0, int k0, int n0, LAS float* scr, int lane) {
;     f32x4 v[8];
; #pragma unroll
;     for (int i = 0; i < 8; ++i) v[i] = *(const f32x4*)(W + (size_t)(k0 + i * 4 + (lane >> 4)) * N + n0 + 4 * (lane & 15));
; #pragma unroll
;     for (int i = 0; i < 8; ++i) { const int kk = i * 4 + (lane >> 4); const float sc = ks ? ks[k0 + kk] : 1.0f; LAS float* d = scr + kk * 65 + 4 * (lane & 15);
;         d[0] = v[i][0] * sc; d[1] = v[i][1] * sc; d[2] = v[i][2] * sc; d[3] = v[i][3] * sc; }
;     asm volatile("s_waitcnt lgkmcnt(0)" ::: "memory");
;     const int kc = lane & 3;
; __device__ __forceinline__ void convert_weights(const Params& p, LAS unsigned char* lds, int first, int last, int worker, int nworkers) {
;     int tid = threadIdx.x; asm volatile("" : "+v"(tid));
;     const int lane = tid & 63, wid = __builtin_amdgcn_readfirstlane(tid >> 6);
;     LAS float* scr = (LAS float*)(lds + wid * 16384);
; #pragma unroll 1
;     for (int it = first + worker; it < last; it += nworkers) {
;         const int l = it / WI_L; int r = it % WI_L;
;         unsigned char* wb = p.ws + WS_W + (size_t)l * W_LAYER;
;         if (r < WI_IN) { const int kb = r / 52, nb = r % 52; transpose_item(p.w_in + (size_t)l * DM * INW, INW, p.norm_mix + l * DM, (bf16_t*)(wb + WO_IN), DM, nb * 64, kb * 32, nb * 64, scr, lane); continue; } r -= WI_IN;
.LBB0_51:
	v_readlane_b32 s52, v249, 4
	v_readlane_b32 s64, v249, 16
	v_readlane_b32 s65, v249, 17
	s_cmp_lg_u64 s[64:65], 0
	s_cselect_b64 s[28:29], -1, 0
	v_mov_b32_e32 v0, v222
	v_cndmask_b32_e64 v1, 0, 1, s[28:29]
	s_cmpk_gt_i32 s0, 0x67f
	v_readfirstlane_b32 s4, v0
	v_cmp_ne_u32_e64 s[30:31], 1, v1
	v_readlane_b32 s53, v249, 5
	v_readlane_b32 s54, v249, 6
	v_readlane_b32 s55, v249, 7
	v_readlane_b32 s56, v249, 8
	v_readlane_b32 s57, v249, 9
	v_readlane_b32 s58, v249, 10
	v_readlane_b32 s59, v249, 11
	v_readlane_b32 s60, v249, 12
	v_readlane_b32 s61, v249, 13
	v_readlane_b32 s62, v249, 14
	v_readlane_b32 s63, v249, 15
	v_readlane_b32 s66, v249, 18
	v_readlane_b32 s67, v249, 19
	s_lshr_b32 s32, s4, 6
	s_sub_i32 s32, s32, 5
	s_mul_i32 s33, s81, 3
	s_add_i32 s33, s33, s32
	s_cmp_lt_i32 s32, 0
	s_cbranch_scc1 .LBB0_65
	s_mul_i32 s32, s92, 3
	s_cmpk_gt_i32 s33, 0x67f
	s_cbranch_scc1 .LBB0_65
	s_add_u32 s1, s50, 0x100000
	s_addc_u32 s12, s51, 0
	s_lshl_b32 s4, s4, 8
	v_lshlrev_b32_e32 v4, 3, v0
	s_and_b32 s4, s4, 0xffffc000
	v_and_b32_e32 v4, 24, v4
	s_add_i32 s4, s4, 0
	v_bfe_u32 v32, v0, 4, 2
	v_lshlrev_b32_e32 v1, 2, v0
	v_bfe_u32 v43, v0, 2, 4
	v_mul_u32_u24_e32 v5, 0x104, v4
	v_and_b32_e32 v0, 60, v0
	v_and_b32_e32 v2, 60, v1
	v_add3_u32 v44, s4, v5, v0
	v_or_b32_e32 v0, 4, v32
	v_mov_b32_e32 v35, 0
	v_lshl_add_u32 v1, v2, 2, s4
	v_mul_u32_u24_e32 v3, 0x104, v32
	v_mul_u32_u24_e32 v0, 0x104, v0
	v_or_b32_e32 v45, 16, v43
	v_or_b32_e32 v46, 32, v43
	v_or_b32_e32 v47, 48, v43
	v_mov_b32_e32 v33, v35
	v_lshlrev_b32_e32 v36, 2, v2
	v_mov_b32_e32 v37, v35
	s_mov_b32 s13, 0xd000
	s_mov_b32 s14, 0x1a000
	s_mov_b32 s15, 0x27000
	s_mov_b32 s16, 0x34000
	v_add_u32_e32 v48, v1, v3
	v_lshlrev_b32_e32 v34, 1, v4
	v_add_u32_e32 v49, v1, v0
	s_mov_b32 s17, s33
	s_branch .LBB0_55

; __device__ __forceinline__ unsigned cvt_pk_bf16(float lo, float hi) { unsigned r; asm volatile("v_cvt_pk_bf16_f32 %0, %1, %2" : "=v"(r) : "v"(lo), "v"(hi)); return r; }
; __device__ __forceinline__ void prologue(const Params& p, LAS unsigned char* lds) {
;     ...
;     {
;         bf16_t* XB = (bf16_t*)(p.ws + WS_XB);
;         const int gw = blockIdx.x * 8 + wid, NGW = gridDim.x * 8;
; #pragma unroll 1
;         for (int m0 = gw; m0 < MREAL; m0 += 4 * NGW) {
;             f32x4 v[4][4];
; #pragma unroll
;             for (int r = 0; r < 4; ++r) { const int m = m0 + r * NGW;
;                 if (m < MREAL) { const f32x4* xr = (const f32x4*)(m < MP ? p.xp + (size_t)m * DM : p.xs + (size_t)(m - MP) * DM) + lane;
; #pragma unroll
;                     for (int j = 0; j < 4; ++j) v[r][j] = xr[64 * j]; } }
; #pragma unroll
;             for (int r = 0; r < 4; ++r) { const int m = m0 + r * NGW;
;                 if (m < MREAL) { float s = 0.f; u32x2* o8 = (u32x2*)(XB + (size_t)m * DM) + lane;
; #pragma unroll
;                     for (int j = 0; j < 4; ++j) { s += (v[r][j][0] * v[r][j][0] + v[r][j][1] * v[r][j][1]) + (v[r][j][2] * v[r][j][2] + v[r][j][3] * v[r][j][3]);
;                         u32x2 w; w.x = cvt_pk_bf16(v[r][j][0], v[r][j][1]); w.y = cvt_pk_bf16(v[r][j][2], v[r][j][3]); o8[64 * j] = w; }
;                     s = wave_sum(s);
;                     if (lane == 0) ssq[m] = s; } }
.LBB0_65:
	v_readfirstlane_b32 s32, v222
	v_mbcnt_lo_u32_b32 v68, -1, 0
	s_lshr_b32 s32, s32, 6
	s_cmp_gt_u32 s32, 4
	s_cbranch_scc1 .LBB0_88
	s_mul_i32 s0, s81, 5
	s_add_i32 s0, s0, s32
	s_mul_i32 s6, s92, 5
	s_cmp_gt_i32 s0, 0x807f
	s_cbranch_scc1 .LBB0_88
	v_lshlrev_b32_e32 v64, 3, v39
	v_mov_b32_e32 v65, 0
	v_lshl_add_u64 v[0:1], s[50:51], 0, v[64:65]
	s_mov_b64 s[4:5], 0x3800000
	v_lshl_add_u64 v[66:67], v[0:1], 0, s[4:5]
	v_cmp_eq_u32_e64 s[4:5], 0, v39
	s_mul_i32 s23, s92, 10
	s_mul_i32 s24, s92, 15
	v_lshlrev_b32_e32 v64, 4, v39
	v_mbcnt_hi_u32_b32 v69, -1, v68
	s_branch .LBB0_69
